# batched residual/FFT-B epilogue loads; LDS loads hoisted and renamed in mLSTM chunk loop (KT transpose, S^T, num/state MFMA sections)
# speedup vs baseline: 1.0180x; 1.0180x over previous
.LBB0_514:
	s_cmp_lt_u32 s63, 3
	s_cselect_b64 s[52:53], -1, 0
	s_add_i32 s50, s61, s63
	s_ashr_i32 s51, s50, 31
	s_lshl_b64 s[48:49], s[50:51], 16
	s_add_u32 s6, s18, s48
	v_add_u32_e32 v14, s33, v1
	s_addc_u32 s51, s30, s49
	ds_read_b128 v[2:5], v14
	ds_read_b128 v[6:9], v14 offset:1024
	ds_read_b128 v[10:13], v14 offset:2048
	ds_read_b128 v[14:17], v14 offset:3072
	s_and_b64 s[48:49], s[52:53], exec
	s_cselect_b32 s37, s51, s37
	s_cselect_b32 s36, s6, s36
	s_cselect_b32 s49, s11, s15
	s_cselect_b32 s48, s10, s14
	s_add_u32 s54, s14, 0x8080
	s_addc_u32 s55, s15, 0
	s_add_u32 s14, s48, 0x8000
	s_addc_u32 s15, s49, 0
	s_add_u32 s64, s36, 0x8000
	s_addc_u32 s65, s37, 0
	v_lshl_add_u64 v[50:51], s[54:55], 0, v[66:67]
	s_add_i32 m0, s35, 0xc000
	ds_read_b128 v[18:21], v85
	ds_read_b128 v[22:25], v85 offset:1024
	ds_read_b128 v[26:29], v85 offset:2048
	ds_read_b128 v[30:33], v85 offset:3072
	ds_read_b128 v[34:37], v85 offset:4096
	ds_read_b128 v[38:41], v85 offset:5120
	ds_read_b128 v[42:45], v85 offset:6144
	ds_read_b128 v[46:49], v85 offset:7168
	global_load_lds_dwordx4 v[50:51], off
	v_lshl_add_u64 v[50:51], s[54:55], 0, v[70:71]
	s_add_i32 m0, s35, 0xe000
	s_nop 0
	global_load_lds_dwordx4 v[50:51], off
	s_waitcnt lgkmcnt(8)
	s_barrier
	s_waitcnt lgkmcnt(0)
	s_setprio 1
	s_waitcnt lgkmcnt(0)
	v_mfma_f32_16x16x32_bf16 v[58:61], v[2:5], v[26:29], 0
	v_mfma_f32_16x16x32_bf16 v[86:89], v[6:9], v[30:33], v[58:61]
	v_mfma_f32_16x16x32_bf16 v[58:61], v[10:13], v[26:29], 0
	v_mfma_f32_16x16x32_bf16 v[50:53], v[2:5], v[18:21], 0
	v_mfma_f32_16x16x32_bf16 v[90:93], v[14:17], v[30:33], v[58:61]
	v_mfma_f32_16x16x32_bf16 v[58:61], v[2:5], v[34:37], 0
	v_mfma_f32_16x16x32_bf16 v[2:5], v[2:5], v[42:45], 0
	v_mfma_f32_16x16x32_bf16 v[50:53], v[6:9], v[22:25], v[50:53]
	v_mfma_f32_16x16x32_bf16 v[54:57], v[10:13], v[18:21], 0
	v_mfma_f32_16x16x32_bf16 v[94:97], v[6:9], v[38:41], v[58:61]
	v_mfma_f32_16x16x32_bf16 v[2:5], v[6:9], v[46:49], v[2:5]
	v_mfma_f32_16x16x32_bf16 v[6:9], v[10:13], v[42:45], 0
	v_mfma_f32_16x16x32_bf16 v[54:57], v[14:17], v[22:25], v[54:57]
	v_mfma_f32_16x16x32_bf16 v[58:61], v[10:13], v[34:37], 0
	v_mfma_f32_16x16x32_bf16 v[6:9], v[14:17], v[46:49], v[6:9]
	v_mfma_f32_16x16x32_bf16 v[98:101], v[14:17], v[38:41], v[58:61]
	s_setprio 0
	s_barrier
	s_add_i32 s6, 0, 0x14000
	s_add_i32 s51, s33, s27
	v_add_u32_e32 v62, s6, v1
	v_lshl_add_u64 v[82:83], s[36:37], 0, v[68:69]
	s_mov_b32 m0, s51
	ds_read_b128 v[10:13], v62
	ds_read_b128 v[14:17], v62 offset:1024
	ds_read_b128 v[58:61], v62 offset:2048
	ds_read_b128 v[62:65], v62 offset:3072
	global_load_lds_dwordx4 v[82:83], off
	v_lshl_add_u64 v[158:159], s[36:37], 0, v[72:73]
	s_add_i32 m0, s51, 0x2000
	s_nop 0
	global_load_lds_dwordx4 v[158:159], off
	s_barrier
	s_waitcnt lgkmcnt(0)
	s_setprio 1
	s_waitcnt lgkmcnt(0)
	v_mfma_f32_16x16x32_bf16 v[102:105], v[10:13], v[18:21], 0
	v_mfma_f32_16x16x32_bf16 v[18:21], v[58:61], v[18:21], 0
	v_mfma_f32_16x16x32_bf16 v[102:105], v[14:17], v[22:25], v[102:105]
	v_mfma_f32_16x16x32_bf16 v[18:21], v[62:65], v[22:25], v[18:21]
	v_mfma_f32_16x16x32_bf16 v[22:25], v[10:13], v[26:29], 0
	v_mfma_f32_16x16x32_bf16 v[26:29], v[58:61], v[26:29], 0
	v_mfma_f32_16x16x32_bf16 v[106:109], v[62:65], v[30:33], v[26:29]
	v_mfma_f32_16x16x32_bf16 v[26:29], v[10:13], v[34:37], 0
	v_mfma_f32_16x16x32_bf16 v[10:13], v[10:13], v[42:45], 0
	v_mfma_f32_16x16x32_bf16 v[22:25], v[14:17], v[30:33], v[22:25]
	v_mfma_f32_16x16x32_bf16 v[110:113], v[14:17], v[38:41], v[26:29]
	v_mfma_f32_16x16x32_bf16 v[26:29], v[58:61], v[34:37], 0
	v_mfma_f32_16x16x32_bf16 v[118:121], v[14:17], v[46:49], v[10:13]
	v_mfma_f32_16x16x32_bf16 v[10:13], v[58:61], v[42:45], 0
	v_mfma_f32_16x16x32_bf16 v[114:117], v[62:65], v[38:41], v[26:29]
	v_mfma_f32_16x16x32_bf16 v[122:125], v[62:65], v[46:49], v[10:13]
	s_setprio 0
	s_mov_b32 m0, s35
	v_lshl_add_u64 v[160:161], s[48:49], 0, v[66:67]
	s_barrier
	global_load_lds_dwordx4 v[160:161], off
	v_lshl_add_u64 v[162:163], s[48:49], 0, v[70:71]
	s_mov_b32 m0, s56
	s_nop 0
	global_load_lds_dwordx4 v[162:163], off
	s_barrier
	s_waitcnt lgkmcnt(0)
	s_setprio 1
	s_setprio 0
	s_barrier
	s_add_i32 s6, s6, s27
	v_lshl_add_u64 v[10:11], s[64:65], 0, v[68:69]
	s_mov_b32 m0, s6
	s_nop 0
	global_load_lds_dwordx4 v[10:11], off
	v_lshl_add_u64 v[10:11], s[64:65], 0, v[72:73]
	s_add_i32 m0, s6, 0x2000
	s_nop 0
	global_load_lds_dwordx4 v[10:11], off
	s_waitcnt vmcnt(6)
	s_barrier
	s_setprio 1
	s_setprio 0
	s_add_i32 s6, 0, 0x18000
	v_add_u32_e32 v26, s6, v1
	s_barrier
	ds_read_b128 v[10:13], v26
	ds_read_b128 v[14:17], v26 offset:1024
	ds_read_b128 v[34:37], v26 offset:2048
	ds_read_b128 v[38:41], v26 offset:3072
	s_mov_b32 m0, s57
	v_lshl_add_u64 v[26:27], s[14:15], 0, v[66:67]
	ds_read_b128 v[126:129], v85 offset:32768
	ds_read_b128 v[130:133], v85 offset:33792
	ds_read_b128 v[134:137], v85 offset:34816
	ds_read_b128 v[138:141], v85 offset:35840
	ds_read_b128 v[142:145], v85 offset:36864
	ds_read_b128 v[146:149], v85 offset:37888
	ds_read_b128 v[150:153], v85 offset:38912
	ds_read_b128 v[154:157], v85 offset:39936
	global_load_lds_dwordx4 v[26:27], off
	v_lshl_add_u64 v[26:27], s[14:15], 0, v[70:71]
	s_mov_b32 m0, s58
	s_nop 0
	global_load_lds_dwordx4 v[26:27], off
	s_waitcnt lgkmcnt(8)
	s_barrier
	s_waitcnt lgkmcnt(0)
	s_setprio 1
	s_waitcnt lgkmcnt(0)
	v_mfma_f32_16x16x32_bf16 v[26:29], v[10:13], v[126:129], v[50:53]
	v_mfma_f32_16x16x32_bf16 v[58:61], v[14:17], v[130:133], v[26:29]
	v_mfma_f32_16x16x32_bf16 v[26:29], v[34:37], v[126:129], v[54:57]
	v_mfma_f32_16x16x32_bf16 v[62:65], v[38:41], v[130:133], v[26:29]
	v_mfma_f32_16x16x32_bf16 v[26:29], v[10:13], v[134:137], v[86:89]
	v_mfma_f32_16x16x32_bf16 v[42:45], v[14:17], v[138:141], v[26:29]
	v_mfma_f32_16x16x32_bf16 v[26:29], v[34:37], v[134:137], v[90:93]
	v_mfma_f32_16x16x32_bf16 v[2:5], v[10:13], v[150:153], v[2:5]
	v_mfma_f32_16x16x32_bf16 v[46:49], v[38:41], v[138:141], v[26:29]
	v_mfma_f32_16x16x32_bf16 v[26:29], v[10:13], v[142:145], v[94:97]
	v_mfma_f32_16x16x32_bf16 v[30:33], v[34:37], v[142:145], v[98:101]
	v_mfma_f32_16x16x32_bf16 v[10:13], v[14:17], v[154:157], v[2:5]
	v_mfma_f32_16x16x32_bf16 v[2:5], v[34:37], v[150:153], v[6:9]
	v_mfma_f32_16x16x32_bf16 v[26:29], v[14:17], v[146:149], v[26:29]
	v_mfma_f32_16x16x32_bf16 v[30:33], v[38:41], v[146:149], v[30:33]
	v_mfma_f32_16x16x32_bf16 v[14:17], v[38:41], v[154:157], v[2:5]
	s_setprio 0
	s_barrier
	s_add_i32 s51, 0, 0x1c000
	v_add_u32_e32 v34, s51, v1
	s_add_i32 s6, s6, s27
	ds_read_b128 v[2:5], v34
	ds_read_b128 v[6:9], v34 offset:1024
	ds_read_b128 v[86:89], v34 offset:2048
	ds_read_b128 v[90:93], v34 offset:3072
	v_lshl_add_u64 v[34:35], v[82:83], 0, s[24:25]
	s_mov_b32 m0, s6
	s_nop 0
	global_load_lds_dwordx4 v[34:35], off
	v_lshl_add_u64 v[34:35], v[158:159], 0, s[24:25]
	s_add_i32 m0, s6, 0x2000
	s_nop 0
	global_load_lds_dwordx4 v[34:35], off
	s_barrier
	s_waitcnt lgkmcnt(0)
	s_setprio 1
	s_waitcnt lgkmcnt(0)
	v_mfma_f32_16x16x32_bf16 v[18:21], v[86:89], v[126:129], v[18:21]
	v_mfma_f32_16x16x32_bf16 v[34:37], v[2:5], v[126:129], v[102:105]
	v_mfma_f32_16x16x32_bf16 v[54:57], v[90:93], v[130:133], v[18:21]
	v_mfma_f32_16x16x32_bf16 v[18:21], v[2:5], v[134:137], v[22:25]
	v_mfma_f32_16x16x32_bf16 v[50:53], v[6:9], v[130:133], v[34:37]
	v_mfma_f32_16x16x32_bf16 v[34:37], v[6:9], v[138:141], v[18:21]
	v_mfma_f32_16x16x32_bf16 v[18:21], v[86:89], v[134:137], v[106:109]
	v_mfma_f32_16x16x32_bf16 v[38:41], v[90:93], v[138:141], v[18:21]
	v_mfma_f32_16x16x32_bf16 v[18:21], v[2:5], v[142:145], v[110:113]
	v_mfma_f32_16x16x32_bf16 v[2:5], v[2:5], v[150:153], v[118:121]
	v_mfma_f32_16x16x32_bf16 v[18:21], v[6:9], v[146:149], v[18:21]
	v_mfma_f32_16x16x32_bf16 v[22:25], v[86:89], v[142:145], v[114:117]
	v_mfma_f32_16x16x32_bf16 v[6:9], v[6:9], v[154:157], v[2:5]
	v_mfma_f32_16x16x32_bf16 v[2:5], v[86:89], v[150:153], v[122:125]
	v_mfma_f32_16x16x32_bf16 v[22:25], v[90:93], v[146:149], v[22:25]
	v_mfma_f32_16x16x32_bf16 v[2:5], v[90:93], v[154:157], v[2:5]
	s_setprio 0
	s_mov_b32 m0, s59
	v_lshl_add_u64 v[82:83], v[160:161], 0, s[24:25]
	s_barrier
	global_load_lds_dwordx4 v[82:83], off
	v_lshl_add_u64 v[82:83], v[162:163], 0, s[24:25]
	s_mov_b32 m0, s60
	s_nop 0
	global_load_lds_dwordx4 v[82:83], off
	s_barrier
	s_waitcnt lgkmcnt(0)
	s_setprio 1
	s_add_u32 s14, s36, 0x8080
	s_addc_u32 s15, s37, 0
	s_setprio 0
	s_barrier
	s_add_i32 s6, s51, s27
	v_lshl_add_u64 v[82:83], s[14:15], 0, v[68:69]
	s_mov_b32 m0, s6
	s_nop 0
	global_load_lds_dwordx4 v[82:83], off
	v_lshl_add_u64 v[82:83], s[14:15], 0, v[72:73]
	s_add_i32 m0, s6, 0x2000
	s_nop 0
	global_load_lds_dwordx4 v[82:83], off
	s_waitcnt vmcnt(6)
	s_barrier
	s_setprio 1
	s_setprio 0
	s_andn2_b64 vcc, exec, s[42:43]
	s_barrier
	s_cbranch_vccnz .LBB0_516
	s_lshl_b32 s6, s26, 8
	s_ashr_i32 s14, s26, 8
	s_and_b32 s6, s6, 0x300
	s_bfe_u32 s15, s26, 0x60002
	v_or_b32_e32 v82, s6, v84
	s_mul_hi_i32 s6, s14, 0x1100
	s_mulk_i32 s14, 0x1100
	s_or_b32 s14, s14, s15
	s_add_u32 s54, s14, 0x100
	s_addc_u32 s55, s6, 0
	v_mov_b32_e32 v83, v0
	v_lshl_add_u64 v[86:87], s[54:55], 0, v[74:75]
	v_lshl_add_u64 v[82:83], v[82:83], 1, s[46:47]
	v_lshlrev_b64 v[86:87], 11, v[86:87]
	v_lshl_add_u64 v[90:91], v[82:83], 0, v[86:87]
	s_barrier
	v_lshl_add_u64 v[94:95], s[54:55], 0, v[76:77]
	v_lshlrev_b64 v[94:95], 11, v[94:95]
	v_lshl_add_u64 v[94:95], v[82:83], 0, v[94:95]
	v_lshl_add_u64 v[96:97], s[54:55], 0, v[78:79]
	v_lshlrev_b64 v[96:97], 11, v[96:97]
	v_lshl_add_u64 v[96:97], v[82:83], 0, v[96:97]
	v_lshl_add_u64 v[98:99], s[54:55], 0, v[80:81]
	v_lshlrev_b64 v[98:99], 11, v[98:99]
	v_lshl_add_u64 v[98:99], v[82:83], 0, v[98:99]
	global_load_dwordx4 v[100:103], v[90:91], off
	global_load_dwordx4 v[104:107], v[90:91], off offset:256
	global_load_dwordx4 v[108:111], v[94:95], off
	global_load_dwordx4 v[112:115], v[94:95], off offset:256
	global_load_dwordx4 v[116:119], v[96:97], off
	global_load_dwordx4 v[120:123], v[96:97], off offset:256
	global_load_dwordx4 v[124:127], v[98:99], off
	global_load_dwordx4 v[128:131], v[98:99], off offset:256
	s_mov_b32 s6, 0x3a800000
	v_pk_mul_f32 v[58:59], v[58:59], s[6:7] op_sel_hi:[1,0]
	v_pk_mul_f32 v[60:61], v[60:61], s[6:7] op_sel_hi:[1,0]
	v_pk_mul_f32 v[62:63], v[62:63], s[6:7] op_sel_hi:[1,0]
	v_pk_mul_f32 v[64:65], v[64:65], s[6:7] op_sel_hi:[1,0]
	v_pk_mul_f32 v[50:51], v[50:51], s[6:7] op_sel_hi:[1,0]
	v_pk_mul_f32 v[52:53], v[52:53], s[6:7] op_sel_hi:[1,0]
	v_pk_mul_f32 v[54:55], v[54:55], s[6:7] op_sel_hi:[1,0]
	v_pk_mul_f32 v[56:57], v[56:57], s[6:7] op_sel_hi:[1,0]
	v_pk_mul_f32 v[42:43], v[42:43], s[6:7] op_sel_hi:[1,0]
	v_pk_mul_f32 v[44:45], v[44:45], s[6:7] op_sel_hi:[1,0]
	v_pk_mul_f32 v[46:47], v[46:47], s[6:7] op_sel_hi:[1,0]
	v_pk_mul_f32 v[48:49], v[48:49], s[6:7] op_sel_hi:[1,0]
	v_pk_mul_f32 v[34:35], v[34:35], s[6:7] op_sel_hi:[1,0]
	v_pk_mul_f32 v[36:37], v[36:37], s[6:7] op_sel_hi:[1,0]
	v_pk_mul_f32 v[38:39], v[38:39], s[6:7] op_sel_hi:[1,0]
	v_pk_mul_f32 v[40:41], v[40:41], s[6:7] op_sel_hi:[1,0]
	v_pk_mul_f32 v[26:27], v[26:27], s[6:7] op_sel_hi:[1,0]
	v_pk_mul_f32 v[28:29], v[28:29], s[6:7] op_sel_hi:[1,0]
	v_pk_mul_f32 v[30:31], v[30:31], s[6:7] op_sel_hi:[1,0]
	v_pk_mul_f32 v[32:33], v[32:33], s[6:7] op_sel_hi:[1,0]
	v_pk_mul_f32 v[18:19], v[18:19], s[6:7] op_sel_hi:[1,0]
	v_pk_mul_f32 v[20:21], v[20:21], s[6:7] op_sel_hi:[1,0]
	v_pk_mul_f32 v[22:23], v[22:23], s[6:7] op_sel_hi:[1,0]
	v_pk_mul_f32 v[24:25], v[24:25], s[6:7] op_sel_hi:[1,0]
	v_pk_mul_f32 v[10:11], v[10:11], s[6:7] op_sel_hi:[1,0]
	v_pk_mul_f32 v[12:13], v[12:13], s[6:7] op_sel_hi:[1,0]
	v_pk_mul_f32 v[14:15], v[14:15], s[6:7] op_sel_hi:[1,0]
	v_pk_mul_f32 v[16:17], v[16:17], s[6:7] op_sel_hi:[1,0]
	v_pk_mul_f32 v[6:7], v[6:7], s[6:7] op_sel_hi:[1,0]
	v_pk_mul_f32 v[8:9], v[8:9], s[6:7] op_sel_hi:[1,0]
	v_pk_mul_f32 v[2:3], v[2:3], s[6:7] op_sel_hi:[1,0]
	v_pk_mul_f32 v[4:5], v[4:5], s[6:7] op_sel_hi:[1,0]
	s_waitcnt vmcnt(7)
	v_lshlrev_b32_e32 v132, 16, v100
	v_and_b32_e32 v133, 0xffff0000, v100
	v_mul_f32_e32 v58, v58, v132
	v_mul_f32_e32 v59, v59, v133
	v_lshlrev_b32_e32 v132, 16, v101
	v_and_b32_e32 v133, 0xffff0000, v101
	v_mul_f32_e32 v60, v60, v132
	v_mul_f32_e32 v61, v61, v133
	v_lshlrev_b32_e32 v132, 16, v102
	v_and_b32_e32 v133, 0xffff0000, v102
	v_mul_f32_e32 v62, v62, v132
	v_mul_f32_e32 v63, v63, v133
	v_lshlrev_b32_e32 v132, 16, v103
	v_and_b32_e32 v133, 0xffff0000, v103
	v_mul_f32_e32 v64, v64, v132
	v_mul_f32_e32 v65, v65, v133
	v_cvt_pk_bf16_f32 v134, v58, v59
	v_cvt_pk_bf16_f32 v135, v60, v61
	v_cvt_pk_bf16_f32 v136, v62, v63
	v_cvt_pk_bf16_f32 v137, v64, v65
	global_store_dwordx4 v[90:91], v[134:137], off
	s_waitcnt vmcnt(7)
	v_lshlrev_b32_e32 v132, 16, v104
	v_and_b32_e32 v133, 0xffff0000, v104
	v_mul_f32_e32 v50, v50, v132
	v_mul_f32_e32 v51, v51, v133
	v_lshlrev_b32_e32 v132, 16, v105
	v_and_b32_e32 v133, 0xffff0000, v105
	v_mul_f32_e32 v52, v52, v132
	v_mul_f32_e32 v53, v53, v133
	v_lshlrev_b32_e32 v132, 16, v106
	v_and_b32_e32 v133, 0xffff0000, v106
	v_mul_f32_e32 v54, v54, v132
	v_mul_f32_e32 v55, v55, v133
	v_lshlrev_b32_e32 v132, 16, v107
	v_and_b32_e32 v133, 0xffff0000, v107
	v_mul_f32_e32 v56, v56, v132
	v_mul_f32_e32 v57, v57, v133
	v_cvt_pk_bf16_f32 v134, v50, v51
	v_cvt_pk_bf16_f32 v135, v52, v53
	v_cvt_pk_bf16_f32 v136, v54, v55
	v_cvt_pk_bf16_f32 v137, v56, v57
	global_store_dwordx4 v[90:91], v[134:137], off offset:256
	s_waitcnt vmcnt(7)
	v_lshlrev_b32_e32 v132, 16, v108
	v_and_b32_e32 v133, 0xffff0000, v108
	v_mul_f32_e32 v42, v42, v132
	v_mul_f32_e32 v43, v43, v133
	v_lshlrev_b32_e32 v132, 16, v109
	v_and_b32_e32 v133, 0xffff0000, v109
	v_mul_f32_e32 v44, v44, v132
	v_mul_f32_e32 v45, v45, v133
	v_lshlrev_b32_e32 v132, 16, v110
	v_and_b32_e32 v133, 0xffff0000, v110
	v_mul_f32_e32 v46, v46, v132
	v_mul_f32_e32 v47, v47, v133
	v_lshlrev_b32_e32 v132, 16, v111
	v_and_b32_e32 v133, 0xffff0000, v111
	v_mul_f32_e32 v48, v48, v132
	v_mul_f32_e32 v49, v49, v133
	v_cvt_pk_bf16_f32 v134, v42, v43
	v_cvt_pk_bf16_f32 v135, v44, v45
	v_cvt_pk_bf16_f32 v136, v46, v47
	v_cvt_pk_bf16_f32 v137, v48, v49
	global_store_dwordx4 v[94:95], v[134:137], off
	s_waitcnt vmcnt(7)
	v_lshlrev_b32_e32 v132, 16, v112
	v_and_b32_e32 v133, 0xffff0000, v112
	v_mul_f32_e32 v34, v34, v132
	v_mul_f32_e32 v35, v35, v133
	v_lshlrev_b32_e32 v132, 16, v113
	v_and_b32_e32 v133, 0xffff0000, v113
	v_mul_f32_e32 v36, v36, v132
	v_mul_f32_e32 v37, v37, v133
	v_lshlrev_b32_e32 v132, 16, v114
	v_and_b32_e32 v133, 0xffff0000, v114
	v_mul_f32_e32 v38, v38, v132
	v_mul_f32_e32 v39, v39, v133
	v_lshlrev_b32_e32 v132, 16, v115
	v_and_b32_e32 v133, 0xffff0000, v115
	v_mul_f32_e32 v40, v40, v132
	v_mul_f32_e32 v41, v41, v133
	v_cvt_pk_bf16_f32 v134, v34, v35
	v_cvt_pk_bf16_f32 v135, v36, v37
	v_cvt_pk_bf16_f32 v136, v38, v39
	v_cvt_pk_bf16_f32 v137, v40, v41
	global_store_dwordx4 v[94:95], v[134:137], off offset:256
	s_waitcnt vmcnt(7)
	v_lshlrev_b32_e32 v132, 16, v116
	v_and_b32_e32 v133, 0xffff0000, v116
	v_mul_f32_e32 v26, v26, v132
	v_mul_f32_e32 v27, v27, v133
	v_lshlrev_b32_e32 v132, 16, v117
	v_and_b32_e32 v133, 0xffff0000, v117
	v_mul_f32_e32 v28, v28, v132
	v_mul_f32_e32 v29, v29, v133
	v_lshlrev_b32_e32 v132, 16, v118
	v_and_b32_e32 v133, 0xffff0000, v118
	v_mul_f32_e32 v30, v30, v132
	v_mul_f32_e32 v31, v31, v133
	v_lshlrev_b32_e32 v132, 16, v119
	v_and_b32_e32 v133, 0xffff0000, v119
	v_mul_f32_e32 v32, v32, v132
	v_mul_f32_e32 v33, v33, v133
	v_cvt_pk_bf16_f32 v134, v26, v27
	v_cvt_pk_bf16_f32 v135, v28, v29
	v_cvt_pk_bf16_f32 v136, v30, v31
	v_cvt_pk_bf16_f32 v137, v32, v33
	global_store_dwordx4 v[96:97], v[134:137], off
	s_waitcnt vmcnt(7)
	v_lshlrev_b32_e32 v132, 16, v120
	v_and_b32_e32 v133, 0xffff0000, v120
	v_mul_f32_e32 v18, v18, v132
	v_mul_f32_e32 v19, v19, v133
	v_lshlrev_b32_e32 v132, 16, v121
	v_and_b32_e32 v133, 0xffff0000, v121
	v_mul_f32_e32 v20, v20, v132
	v_mul_f32_e32 v21, v21, v133
	v_lshlrev_b32_e32 v132, 16, v122
	v_and_b32_e32 v133, 0xffff0000, v122
	v_mul_f32_e32 v22, v22, v132
	v_mul_f32_e32 v23, v23, v133
	v_lshlrev_b32_e32 v132, 16, v123
	v_and_b32_e32 v133, 0xffff0000, v123
	v_mul_f32_e32 v24, v24, v132
	v_mul_f32_e32 v25, v25, v133
	v_cvt_pk_bf16_f32 v134, v18, v19
	v_cvt_pk_bf16_f32 v135, v20, v21
	v_cvt_pk_bf16_f32 v136, v22, v23
	v_cvt_pk_bf16_f32 v137, v24, v25
	global_store_dwordx4 v[96:97], v[134:137], off offset:256
	s_waitcnt vmcnt(7)
	v_lshlrev_b32_e32 v132, 16, v124
	v_and_b32_e32 v133, 0xffff0000, v124
	v_mul_f32_e32 v10, v10, v132
	v_mul_f32_e32 v11, v11, v133
	v_lshlrev_b32_e32 v132, 16, v125
	v_and_b32_e32 v133, 0xffff0000, v125
	v_mul_f32_e32 v12, v12, v132
	v_mul_f32_e32 v13, v13, v133
	v_lshlrev_b32_e32 v132, 16, v126
	v_and_b32_e32 v133, 0xffff0000, v126
	v_mul_f32_e32 v14, v14, v132
	v_mul_f32_e32 v15, v15, v133
	v_lshlrev_b32_e32 v132, 16, v127
	v_and_b32_e32 v133, 0xffff0000, v127
	v_mul_f32_e32 v16, v16, v132
	v_mul_f32_e32 v17, v17, v133
	v_cvt_pk_bf16_f32 v134, v10, v11
	v_cvt_pk_bf16_f32 v135, v12, v13
	v_cvt_pk_bf16_f32 v136, v14, v15
	v_cvt_pk_bf16_f32 v137, v16, v17
	global_store_dwordx4 v[98:99], v[134:137], off
	s_waitcnt vmcnt(7)
	v_lshlrev_b32_e32 v132, 16, v128
	v_and_b32_e32 v133, 0xffff0000, v128
	v_mul_f32_e32 v6, v6, v132
	v_mul_f32_e32 v7, v7, v133
	v_lshlrev_b32_e32 v132, 16, v129
	v_and_b32_e32 v133, 0xffff0000, v129
	v_mul_f32_e32 v8, v8, v132
	v_mul_f32_e32 v9, v9, v133
	v_lshlrev_b32_e32 v132, 16, v130
	v_and_b32_e32 v133, 0xffff0000, v130
	v_mul_f32_e32 v2, v2, v132
	v_mul_f32_e32 v3, v3, v133
	v_lshlrev_b32_e32 v132, 16, v131
	v_and_b32_e32 v133, 0xffff0000, v131
	v_mul_f32_e32 v4, v4, v132
	v_mul_f32_e32 v5, v5, v133
	v_cvt_pk_bf16_f32 v134, v6, v7
	v_cvt_pk_bf16_f32 v135, v8, v9
	v_cvt_pk_bf16_f32 v136, v2, v3
	v_cvt_pk_bf16_f32 v137, v4, v5
	global_store_dwordx4 v[98:99], v[134:137], off offset:256
	s_cmp_eq_u32 s63, 3
	s_mov_b64 s[14:15], -1
	s_cbranch_scc1 .LBB0_513
	s_branch .LBB0_517

.LBB0_816:
	s_or_b64 exec, exec, s[14:15]
	ds_read_b128 v[182:185], v157
	ds_read_b128 v[186:189], v157 offset:4352
	ds_read_b128 v[190:193], v156 offset:17472
	ds_read_b128 v[194:197], v157 offset:64
	ds_read_b128 v[198:201], v157 offset:4416
	ds_read_b128 v[202:205], v156 offset:17536
	ds_read_b128 v[206:209], v157 offset:128
	ds_read_b128 v[210:213], v157 offset:4480
	s_waitcnt lgkmcnt(8)
	ds_read_b128 v[178:181], v156 offset:17408
	ds_read_b128 v[214:217], v157 offset:192
	s_waitcnt lgkmcnt(1)
	v_mfma_f32_16x16x32_bf16 v[62:65], v[178:181], v[182:185], 0
	v_mfma_f32_16x16x32_bf16 v[58:61], v[178:181], v[186:189], 0
	v_mfma_f32_16x16x32_bf16 v[62:65], v[190:193], v[194:197], v[62:65]
	v_mfma_f32_16x16x32_bf16 v[58:61], v[190:193], v[198:201], v[58:61]
	v_mfma_f32_16x16x32_bf16 v[62:65], v[202:205], v[206:209], v[62:65]
	v_mfma_f32_16x16x32_bf16 v[58:61], v[202:205], v[210:213], v[58:61]
	ds_read_b128 v[66:69], v156 offset:17600
	s_waitcnt lgkmcnt(0)
	v_mfma_f32_16x16x32_bf16 v[62:65], v[66:69], v[214:217], v[62:65]
	ds_read_b128 v[70:73], v157 offset:4544
	s_waitcnt lgkmcnt(0)
	s_barrier
	v_mfma_f32_16x16x32_bf16 v[58:61], v[66:69], v[70:73], v[58:61]
	ds_read_b32 v68, v117
	v_mov_b32_e32 v66, 0
	v_mov_b32_e32 v67, 0
	s_and_saveexec_b64 s[14:15], s[68:69]
	s_cbranch_execz .LBB0_836
	ds_read_b32 v1, v118
	s_waitcnt lgkmcnt(0)
	v_sub_f32_e32 v1, v1, v68
	v_mul_f32_e32 v1, 0x3fb8aa3b, v1
	v_exp_f32_e32 v1, v1
	s_nop 0
	v_mul_f32_e32 v67, v62, v1
	s_or_b64 exec, exec, s[14:15]
	v_mov_b32_e32 v62, 0
	s_and_saveexec_b64 s[14:15], s[70:71]
	s_cbranch_execnz .LBB0_837

.LBB0_828:
	s_or_b64 exec, exec, s[14:15]
	s_nop 1
	v_cvt_pk_bf16_f32 v60, v1, v63
	s_nop 1
	v_cvt_pk_bf16_f32 v61, v58, v59
	ds_write_b64 v168, v[60:61] offset:2304
	ds_read_b64 v[180:181], v123
	ds_read_b64 v[182:183], v124
	ds_read_u16 v179, v159 offset:17408
	ds_read_u16 v184, v159 offset:17680
	ds_read_u16 v185, v159 offset:17952
	ds_read_u16 v186, v159 offset:18224
	ds_read_b64 v[188:189], v125
	ds_read_u16 v187, v159 offset:18496
	ds_read_u16 v190, v159 offset:18768
	ds_read_b64 v[192:193], v126
	ds_read_u16 v191, v159 offset:19040
	ds_read_u16 v194, v159 offset:19312
	s_waitcnt lgkmcnt(12)
	ds_read_u16 v178, v158 offset:17408
	ds_read_b64 v[196:197], v127
	ds_read_u16 v195, v159 offset:19584
	v_cmp_lt_i32_e32 vcc, v231, v225
	s_and_b32 s35, s35, 1
	s_waitcnt lgkmcnt(2)
	v_lshlrev_b32_e32 v1, 16, v178
	v_mul_f32_e32 v1, v180, v1
	ds_read_u16 v178, v159 offset:19856
	v_lshlrev_b32_e32 v58, 16, v179
	v_mul_f32_e32 v58, v181, v58
	s_nop 1
	v_cvt_pk_bf16_f32 v58, v1, v58
	s_nop 0
	v_lshlrev_b32_e32 v1, 16, v58
	v_and_b32_e32 v59, 0xffff0000, v58
	v_add_f32_e32 v1, v1, v59
	ds_read_b64 v[180:181], v128
	v_add_f32_e32 v1, 0, v1
	v_lshlrev_b32_e32 v59, 16, v184
	v_mul_f32_e32 v59, v182, v59
	ds_read_u16 v179, v159 offset:20128
	v_lshlrev_b32_e32 v60, 16, v185
	v_mul_f32_e32 v60, v183, v60
	s_nop 1
	v_cvt_pk_bf16_f32 v59, v59, v60
	s_nop 0
	v_lshlrev_b32_e32 v60, 16, v59
	v_and_b32_e32 v61, 0xffff0000, v59
	v_add_f32_e32 v60, v60, v61
	v_add_f32_e32 v1, v1, v60
	ds_read_u16 v182, v159 offset:20400
	v_lshlrev_b32_e32 v62, 16, v186
	ds_read_b64 v[184:185], v129
	v_mul_f32_e32 v60, v188, v62
	ds_read_u16 v183, v159 offset:20672
	v_lshlrev_b32_e32 v62, 16, v187
	v_mul_f32_e32 v61, v189, v62
	s_nop 1
	v_cvt_pk_bf16_f32 v60, v60, v61
	s_nop 0
	v_lshlrev_b32_e32 v61, 16, v60
	v_and_b32_e32 v62, 0xffff0000, v60
	v_add_f32_e32 v61, v61, v62
	v_add_f32_e32 v1, v1, v61
	ds_read_u16 v186, v159 offset:20944
	v_lshlrev_b32_e32 v61, 16, v190
	v_mul_f32_e32 v61, v192, v61
	ds_read_u16 v187, v159 offset:21216
	v_lshlrev_b32_e32 v62, 16, v191
	v_mul_f32_e32 v62, v193, v62
	s_nop 1
	v_cvt_pk_bf16_f32 v61, v61, v62
	s_nop 0
	v_lshlrev_b32_e32 v62, 16, v61
	v_and_b32_e32 v63, 0xffff0000, v61
	v_add_f32_e32 v62, v62, v63
	v_add_f32_e32 v1, v1, v62
	v_lshlrev_b32_e32 v64, 16, v194
	s_waitcnt lgkmcnt(9)
	v_mul_f32_e32 v62, v196, v64
	s_waitcnt lgkmcnt(8)
	v_lshlrev_b32_e32 v64, 16, v195
	v_mul_f32_e32 v63, v197, v64
	s_nop 1
	v_cvt_pk_bf16_f32 v62, v62, v63
	s_nop 0
	v_lshlrev_b32_e32 v63, 16, v62
	v_and_b32_e32 v64, 0xffff0000, v62
	v_add_f32_e32 v63, v63, v64
	v_add_f32_e32 v1, v1, v63
	s_waitcnt lgkmcnt(7)
	v_lshlrev_b32_e32 v63, 16, v178
	s_waitcnt lgkmcnt(6)
	v_mul_f32_e32 v63, v180, v63
	s_waitcnt lgkmcnt(5)
	v_lshlrev_b32_e32 v64, 16, v179
	v_mul_f32_e32 v64, v181, v64
	s_nop 1
	v_cvt_pk_bf16_f32 v63, v63, v64
	s_nop 0
	v_lshlrev_b32_e32 v64, 16, v63
	v_and_b32_e32 v65, 0xffff0000, v63
	v_add_f32_e32 v64, v64, v65
	v_add_f32_e32 v1, v1, v64
	s_waitcnt lgkmcnt(4)
	v_lshlrev_b32_e32 v66, 16, v182
	s_waitcnt lgkmcnt(3)
	v_mul_f32_e32 v64, v184, v66
	s_waitcnt lgkmcnt(2)
	v_lshlrev_b32_e32 v66, 16, v183
	v_mul_f32_e32 v65, v185, v66
	s_nop 1
	v_cvt_pk_bf16_f32 v64, v64, v65
	s_nop 0
	v_lshlrev_b32_e32 v65, 16, v64
	v_and_b32_e32 v66, 0xffff0000, v64
	v_add_f32_e32 v65, v65, v66
	v_add_f32_e32 v1, v1, v65
	ds_read_b64 v[66:67], v130
	s_waitcnt lgkmcnt(2)
	v_lshlrev_b32_e32 v65, 16, v186
	s_waitcnt lgkmcnt(0)
	v_mul_f32_e32 v65, v66, v65
	v_lshlrev_b32_e32 v66, 16, v187
	v_mul_f32_e32 v66, v67, v66
	s_nop 1
	v_cvt_pk_bf16_f32 v65, v65, v66
	ds_write_b128 v160, v[58:61] offset:34816
	ds_write_b128 v160, v[62:65] offset:34832
	v_lshlrev_b32_e32 v66, 16, v65
	v_and_b32_e32 v67, 0xffff0000, v65
	v_add_f32_e32 v66, v66, v67
	v_cndmask_b32_e32 v58, v223, v231, vcc
	v_add_f32_e32 v1, v1, v66
	v_lshlrev_b32_e32 v58, 2, v58
	ds_bpermute_b32 v59, v58, v1
	v_cmp_lt_i32_e32 vcc, v230, v225
	s_waitcnt lgkmcnt(0)
	v_add_f32_e32 v1, v1, v59
	v_cndmask_b32_e32 v59, v223, v230, vcc
	v_lshlrev_b32_e32 v59, 2, v59
	ds_bpermute_b32 v61, v59, v1
	s_and_saveexec_b64 s[14:15], s[44:45]
	s_xor_b64 s[14:15], exec, s[14:15]
	s_lshl_b32 s84, s35, 9
	s_or_saveexec_b64 s[14:15], s[14:15]
	v_mov_b32_e32 v60, s84
	s_xor_b64 exec, exec, s[14:15]
	s_cbranch_execz .LBB0_832
	s_lshl_b32 s35, s35, 9
	s_waitcnt lgkmcnt(0)
	v_add_f32_e32 v1, v1, v61
	v_mov_b32_e32 v60, s29
	v_add_u32_e32 v61, s35, v113
	ds_read_b32 v60, v60
	ds_read_b32 v61, v61
	s_xor_b32 s84, s35, 0x200
	s_waitcnt lgkmcnt(0)
	v_fmac_f32_e32 v1, v60, v61
	v_add_u32_e32 v60, s84, v113
	ds_write_b32 v60, v1
	v_mov_b32_e32 v60, s35

.LBB0_834:
	s_or_b64 exec, exec, s[14:15]
	s_waitcnt lgkmcnt(0)
	ds_read_b128 v[182:185], v164
	ds_read_b128 v[186:189], v164 offset:2304
	ds_read_b128 v[190:193], v164 offset:4608
	ds_read_b128 v[194:197], v164 offset:6912
	ds_read_b128 v[198:201], v163 offset:53312
	s_waitcnt lgkmcnt(5)
	ds_read_b128 v[178:181], v163 offset:53248
	ds_read_b128 v[202:205], v164 offset:64
	v_add_u32_e32 v1, v106, v135
	ds_read_b128 v[206:209], v1 offset:8704
	ds_read_b128 v[210:213], v1 offset:13056
	s_waitcnt lgkmcnt(3)
	v_mfma_f32_16x16x32_bf16 v[74:77], v[178:181], v[190:193], 0
	ds_read_b128 v[190:193], v1 offset:4352
	v_mfma_f32_16x16x32_bf16 v[62:65], v[178:181], v[182:185], 0
	v_mfma_f32_16x16x32_bf16 v[66:69], v[178:181], v[186:189], 0
	v_mfma_f32_16x16x32_bf16 v[58:61], v[178:181], v[194:197], 0
	ds_read_b128 v[178:181], v164 offset:2368
	ds_read_b128 v[182:185], v164 offset:4672
	ds_read_b128 v[186:189], v164 offset:6976
	ds_read_b128 v[194:197], v165
	s_waitcnt lgkmcnt(7)
	v_mfma_f32_16x16x32_bf16 v[70:73], v[198:201], v[202:205], v[62:65]
	ds_read_b128 v[202:205], v1
	s_nop 1
	ds_read_b128 v[214:217], v165 offset:64
	s_waitcnt lgkmcnt(5)
	v_mfma_f32_16x16x32_bf16 v[66:69], v[198:201], v[178:181], v[66:69]
	ds_read_b128 v[178:181], v1 offset:64
	s_waitcnt lgkmcnt(5)
	v_mfma_f32_16x16x32_bf16 v[62:65], v[198:201], v[182:185], v[74:77]
	s_nop 2
	ds_read_b128 v[182:185], v1 offset:4416
	s_waitcnt lgkmcnt(5)
	v_mfma_f32_16x16x32_bf16 v[58:61], v[198:201], v[186:189], v[58:61]
	ds_read_b128 v[186:189], v1 offset:8768
	ds_read_b128 v[198:201], v1 offset:13120
	s_waitcnt lgkmcnt(5)
	v_mfma_f32_16x16x32_bf16 v[78:81], v[194:197], v[202:205], 0
	v_mfma_f32_16x16x32_bf16 v[82:85], v[194:197], v[190:193], 0
	v_mfma_f32_16x16x32_bf16 v[86:89], v[194:197], v[206:209], 0
	v_mfma_f32_16x16x32_bf16 v[74:77], v[194:197], v[210:213], 0
	ds_read_b128 v[190:193], v165 offset:128
	ds_read_b128 v[194:197], v1 offset:128
	s_waitcnt lgkmcnt(5)
	v_mfma_f32_16x16x32_bf16 v[78:81], v[214:217], v[178:181], v[78:81]
	ds_read_b128 v[178:181], v1 offset:4480
	s_waitcnt lgkmcnt(5)
	v_mfma_f32_16x16x32_bf16 v[82:85], v[214:217], v[182:185], v[82:85]
	ds_read_b128 v[182:185], v1 offset:8832
	s_waitcnt lgkmcnt(5)
	v_mfma_f32_16x16x32_bf16 v[86:89], v[214:217], v[186:189], v[86:89]
	ds_read_b128 v[186:189], v1 offset:13184
	s_waitcnt lgkmcnt(5)
	v_mfma_f32_16x16x32_bf16 v[74:77], v[214:217], v[198:201], v[74:77]
	ds_read_b128 v[198:201], v1 offset:192
	s_waitcnt lgkmcnt(4)
	v_mfma_f32_16x16x32_bf16 v[78:81], v[190:193], v[194:197], v[78:81]
	ds_read_b128 v[194:197], v1 offset:4544
	s_waitcnt lgkmcnt(4)
	v_mfma_f32_16x16x32_bf16 v[82:85], v[190:193], v[178:181], v[82:85]
	ds_read_b128 v[178:181], v1 offset:8896
	s_waitcnt lgkmcnt(4)
	v_mfma_f32_16x16x32_bf16 v[150:153], v[190:193], v[182:185], v[86:89]
	s_nop 2
	s_waitcnt lgkmcnt(3)
	v_mfma_f32_16x16x32_bf16 v[74:77], v[190:193], v[186:189], v[74:77]
	ds_read_b128 v[146:149], v165 offset:192
	s_waitcnt lgkmcnt(0)
	v_mfma_f32_16x16x32_bf16 v[86:89], v[146:149], v[198:201], v[78:81]
	s_nop 2
	v_mfma_f32_16x16x32_bf16 v[82:85], v[146:149], v[194:197], v[82:85]
	v_mfma_f32_16x16x32_bf16 v[78:81], v[146:149], v[178:181], v[150:153]
	s_nop 2
	ds_read_b128 v[150:153], v1 offset:13248
	s_waitcnt lgkmcnt(0)
	v_mov_b32_e32 v1, s29
	s_waitcnt lgkmcnt(0)
	v_mfma_f32_16x16x32_bf16 v[74:77], v[146:149], v[150:153], v[74:77]
	ds_read_b32 v146, v1
	v_add_u32_e32 v1, v106, v131
	ds_read_b128 v[150:153], v1 offset:53248
	s_waitcnt lgkmcnt(1)
	v_pk_mul_f32 v[28:29], v[28:29], v[146:147] op_sel_hi:[1,0]
	v_pk_mul_f32 v[26:27], v[26:27], v[146:147] op_sel_hi:[1,0]
	v_pk_mul_f32 v[32:33], v[32:33], v[146:147] op_sel_hi:[1,0]
	v_pk_mul_f32 v[30:31], v[30:31], v[146:147] op_sel_hi:[1,0]
	v_pk_mul_f32 v[36:37], v[36:37], v[146:147] op_sel_hi:[1,0]
	v_pk_mul_f32 v[34:35], v[34:35], v[146:147] op_sel_hi:[1,0]
	v_pk_mul_f32 v[40:41], v[40:41], v[146:147] op_sel_hi:[1,0]
	v_pk_mul_f32 v[38:39], v[38:39], v[146:147] op_sel_hi:[1,0]
	v_pk_mul_f32 v[44:45], v[44:45], v[146:147] op_sel_hi:[1,0]
	v_pk_mul_f32 v[42:43], v[42:43], v[146:147] op_sel_hi:[1,0]
	v_pk_mul_f32 v[48:49], v[48:49], v[146:147] op_sel_hi:[1,0]
	v_pk_mul_f32 v[46:47], v[46:47], v[146:147] op_sel_hi:[1,0]
	v_pk_mul_f32 v[52:53], v[52:53], v[146:147] op_sel_hi:[1,0]
	v_pk_mul_f32 v[50:51], v[50:51], v[146:147] op_sel_hi:[1,0]
	v_pk_mul_f32 v[56:57], v[56:57], v[146:147] op_sel_hi:[1,0]
	v_pk_mul_f32 v[54:55], v[54:55], v[146:147] op_sel_hi:[1,0]
	ds_read_b128 v[182:185], v1 offset:55552
	ds_read_b128 v[186:189], v1 offset:57856
	ds_read_b128 v[190:193], v1 offset:60160
	ds_read_b128 v[194:197], v166 offset:53248
	ds_read_b128 v[198:201], v166 offset:55552
	ds_read_b128 v[202:205], v166 offset:57856
	s_waitcnt lgkmcnt(6)
	ds_read_b128 v[178:181], v163 offset:34816
	s_waitcnt lgkmcnt(0)
	v_mfma_f32_16x16x32_bf16 v[26:29], v[178:181], v[150:153], v[26:29]
	ds_read_b128 v[206:209], v166 offset:60160
	v_mfma_f32_16x16x32_bf16 v[30:33], v[178:181], v[182:185], v[30:33]
	v_mfma_f32_16x16x32_bf16 v[34:37], v[178:181], v[186:189], v[34:37]
	ds_read_b128 v[182:185], v1 offset:53312
	v_mfma_f32_16x16x32_bf16 v[38:41], v[178:181], v[190:193], v[38:41]
	ds_read_b128 v[186:189], v1 offset:55616
	v_mfma_f32_16x16x32_bf16 v[42:45], v[178:181], v[194:197], v[42:45]
	ds_read_b128 v[190:193], v1 offset:57920
	v_mfma_f32_16x16x32_bf16 v[46:49], v[178:181], v[198:201], v[46:49]
	ds_read_b128 v[194:197], v1 offset:60224
	v_mfma_f32_16x16x32_bf16 v[50:53], v[178:181], v[202:205], v[50:53]
	ds_read_b128 v[198:201], v166 offset:53312
	s_waitcnt lgkmcnt(5)
	v_mfma_f32_16x16x32_bf16 v[54:57], v[178:181], v[206:209], v[54:57]
	ds_read_b128 v[178:181], v166 offset:55616
	ds_read_b128 v[146:149], v163 offset:34880
	ds_read_b128 v[202:205], v166 offset:57920
	s_waitcnt lgkmcnt(1)
	v_mfma_f32_16x16x32_bf16 v[26:29], v[146:149], v[182:185], v[26:29]
	v_mfma_f32_16x16x32_bf16 v[30:33], v[146:149], v[186:189], v[30:33]
	v_mfma_f32_16x16x32_bf16 v[34:37], v[146:149], v[190:193], v[34:37]
	v_mfma_f32_16x16x32_bf16 v[38:41], v[146:149], v[194:197], v[38:41]
	v_mfma_f32_16x16x32_bf16 v[42:45], v[146:149], v[198:201], v[42:45]
	v_mfma_f32_16x16x32_bf16 v[46:49], v[146:149], v[178:181], v[46:49]
	s_waitcnt lgkmcnt(0)
	v_mfma_f32_16x16x32_bf16 v[50:53], v[146:149], v[202:205], v[50:53]
	ds_read_b128 v[150:153], v166 offset:60224
	s_waitcnt lgkmcnt(0)
	s_barrier
	v_mfma_f32_16x16x32_bf16 v[54:57], v[146:149], v[150:153], v[54:57]
	ds_read_b32 v1, v136
	ds_read_b32 v146, v137
	ds_read_b32 v147, v138
	s_waitcnt lgkmcnt(2)
	v_fma_f32 v70, v86, v1, v70
	s_waitcnt lgkmcnt(1)
	v_max_f32_e64 v146, |v146|, |v146|
	s_waitcnt lgkmcnt(0)
	v_max_f32_e32 v147, v147, v147
	v_max_f32_e32 v146, v146, v147
	v_div_scale_f32 v147, s[14:15], v146, v146, 1.0
	v_rcp_f32_e32 v148, v147
	v_fma_f32 v71, v87, v1, v71
	v_fma_f32 v72, v88, v1, v72
	v_fmac_f32_e32 v73, v89, v1
	v_fma_f32 v149, -v147, v148, 1.0
	v_fmac_f32_e32 v148, v149, v148
	v_div_scale_f32 v149, vcc, 1.0, v146, 1.0
	v_mul_f32_e32 v150, v149, v148
	v_fma_f32 v151, -v147, v150, v149
	v_fmac_f32_e32 v150, v151, v148
	v_fma_f32 v147, -v147, v150, v149
	v_div_fmas_f32 v147, v147, v148, v150
	v_div_fixup_f32 v146, v147, v146, 1.0
	v_mul_f32_e32 v70, v70, v146
	v_mul_f32_e32 v71, v71, v146
	v_mul_f32_e32 v72, v72, v146
	v_mul_f32_e32 v1, v73, v146
	s_nop 1
	v_cvt_pk_bf16_f32 v70, v70, v71
	s_nop 1
	v_cvt_pk_bf16_f32 v71, v72, v1
	v_add_u32_e32 v72, s18, v101
	v_mov_b32_e32 v73, v0
	v_lshlrev_b64 v[72:73], 11, v[72:73]
	v_lshl_add_u64 v[72:73], v[98:99], 0, v[72:73]
	global_store_dwordx2 v[72:73], v[70:71], off sc1
	ds_read_b32 v1, v139
	ds_read_b32 v70, v140
	ds_read_b32 v71, v141
	s_waitcnt lgkmcnt(2)
	v_fma_f32 v66, v82, v1, v66
	s_waitcnt lgkmcnt(1)
	v_max_f32_e64 v70, |v70|, |v70|
	s_waitcnt lgkmcnt(0)
	v_max_f32_e32 v71, v71, v71
	v_max_f32_e32 v70, v70, v71
	v_div_scale_f32 v71, s[14:15], v70, v70, 1.0
	v_rcp_f32_e32 v72, v71
	v_fma_f32 v67, v83, v1, v67
	v_fma_f32 v68, v84, v1, v68
	v_fmac_f32_e32 v69, v85, v1
	v_fma_f32 v73, -v71, v72, 1.0
	v_fmac_f32_e32 v72, v73, v72
	v_div_scale_f32 v73, vcc, 1.0, v70, 1.0
	v_mul_f32_e32 v86, v73, v72
	v_fma_f32 v87, -v71, v86, v73
	v_fmac_f32_e32 v86, v87, v72
	v_fma_f32 v71, -v71, v86, v73
	v_div_fmas_f32 v71, v71, v72, v86
	v_div_fixup_f32 v70, v71, v70, 1.0
	v_mul_f32_e32 v66, v66, v70
	v_mul_f32_e32 v67, v67, v70
	v_mul_f32_e32 v68, v68, v70
	v_mul_f32_e32 v1, v69, v70
	s_nop 1
	v_cvt_pk_bf16_f32 v66, v66, v67
	s_nop 1
	v_cvt_pk_bf16_f32 v67, v68, v1
	v_add_u32_e32 v68, s18, v132
	v_mov_b32_e32 v69, v0
	v_lshlrev_b64 v[68:69], 11, v[68:69]
	v_lshl_add_u64 v[68:69], v[98:99], 0, v[68:69]
	global_store_dwordx2 v[68:69], v[66:67], off sc1
	ds_read_b32 v1, v142
	ds_read_b32 v66, v143
	ds_read_b32 v67, v144
	s_waitcnt lgkmcnt(2)
	v_fma_f32 v62, v78, v1, v62
	s_waitcnt lgkmcnt(1)
	v_max_f32_e64 v66, |v66|, |v66|
	s_waitcnt lgkmcnt(0)
	v_max_f32_e32 v67, v67, v67
	v_max_f32_e32 v66, v66, v67
	v_div_scale_f32 v67, s[14:15], v66, v66, 1.0
	v_rcp_f32_e32 v68, v67
	v_fma_f32 v63, v79, v1, v63
	v_fma_f32 v64, v80, v1, v64
	v_fmac_f32_e32 v65, v81, v1
	v_fma_f32 v69, -v67, v68, 1.0
	v_fmac_f32_e32 v68, v69, v68
	v_div_scale_f32 v69, vcc, 1.0, v66, 1.0
	v_mul_f32_e32 v70, v69, v68
	v_fma_f32 v71, -v67, v70, v69
	v_fmac_f32_e32 v70, v71, v68
	v_fma_f32 v67, -v67, v70, v69
	v_div_fmas_f32 v67, v67, v68, v70
	v_div_fixup_f32 v66, v67, v66, 1.0
	v_mul_f32_e32 v62, v62, v66
	v_mul_f32_e32 v63, v63, v66
	v_mul_f32_e32 v64, v64, v66
	v_mul_f32_e32 v1, v65, v66
	s_nop 1
	v_cvt_pk_bf16_f32 v62, v62, v63
	s_nop 1
	v_cvt_pk_bf16_f32 v63, v64, v1
	v_add_u32_e32 v64, s18, v133
	v_mov_b32_e32 v65, v0
	v_lshlrev_b64 v[64:65], 11, v[64:65]
	v_lshl_add_u64 v[64:65], v[98:99], 0, v[64:65]
	global_store_dwordx2 v[64:65], v[62:63], off sc1
	ds_read_b32 v1, v145
	ds_read_b32 v62, v154
	ds_read_b32 v63, v155
	s_waitcnt lgkmcnt(2)
	v_fma_f32 v58, v74, v1, v58
	s_waitcnt lgkmcnt(1)
	v_max_f32_e64 v62, |v62|, |v62|
	s_waitcnt lgkmcnt(0)
	v_max_f32_e32 v63, v63, v63
	v_max_f32_e32 v62, v62, v63
	v_div_scale_f32 v63, s[14:15], v62, v62, 1.0
	v_rcp_f32_e32 v64, v63
	v_fma_f32 v59, v75, v1, v59
	v_fma_f32 v60, v76, v1, v60
	v_fmac_f32_e32 v61, v77, v1
	v_fma_f32 v65, -v63, v64, 1.0
	v_fmac_f32_e32 v64, v65, v64
	v_div_scale_f32 v65, vcc, 1.0, v62, 1.0
	v_mul_f32_e32 v66, v65, v64
	v_fma_f32 v67, -v63, v66, v65
	v_fmac_f32_e32 v66, v67, v64
	v_fma_f32 v63, -v63, v66, v65
	v_div_fmas_f32 v63, v63, v64, v66
	v_div_fixup_f32 v62, v63, v62, 1.0
	v_mul_f32_e32 v58, v58, v62
	v_mul_f32_e32 v59, v59, v62
	v_mul_f32_e32 v60, v60, v62
	v_mul_f32_e32 v1, v61, v62
	s_nop 1
	v_cvt_pk_bf16_f32 v58, v58, v59
	s_nop 1
	v_cvt_pk_bf16_f32 v59, v60, v1
	v_add_u32_e32 v60, s18, v134
	v_mov_b32_e32 v61, v0
	v_lshlrev_b64 v[60:61], 11, v[60:61]
	v_lshl_add_u64 v[60:61], v[98:99], 0, v[60:61]
	global_store_dwordx2 v[60:61], v[58:59], off sc1
	s_nop 1
	v_cvt_pk_bf16_f32 v58, v26, v27
	s_nop 1
	v_cvt_pk_bf16_f32 v59, v28, v29
	v_add_u32_e32 v1, v116, v135
	ds_write_b64 v1, v[58:59]
	s_nop 1
	v_cvt_pk_bf16_f32 v58, v30, v31
	s_nop 1
	v_cvt_pk_bf16_f32 v59, v32, v33
	ds_write_b64 v1, v[58:59] offset:4352
	s_nop 1
	v_cvt_pk_bf16_f32 v58, v34, v35
	s_nop 1
	v_cvt_pk_bf16_f32 v59, v36, v37
	ds_write_b64 v1, v[58:59] offset:8704
	s_nop 1
	v_cvt_pk_bf16_f32 v58, v38, v39
	s_nop 1
	v_cvt_pk_bf16_f32 v59, v40, v41
	ds_write_b64 v1, v[58:59] offset:13056
	s_nop 1
	v_cvt_pk_bf16_f32 v58, v42, v43
	s_nop 1
	v_cvt_pk_bf16_f32 v59, v44, v45
	ds_write_b64 v167, v[58:59]
	s_nop 1
	v_cvt_pk_bf16_f32 v58, v46, v47
	s_nop 1
	v_cvt_pk_bf16_f32 v59, v48, v49
	ds_write_b64 v167, v[58:59] offset:4352
	s_nop 1
	v_cvt_pk_bf16_f32 v58, v50, v51
	s_nop 1
	v_cvt_pk_bf16_f32 v59, v52, v53
	s_andn2_b64 vcc, exec, s[10:11]
	ds_write_b64 v167, v[58:59] offset:8704
	s_nop 1
	v_cvt_pk_bf16_f32 v58, v54, v55
	s_nop 1
	v_cvt_pk_bf16_f32 v59, v56, v57
	ds_write_b64 v167, v[58:59] offset:13056
	s_cbranch_vccnz .LBB0_786
	s_waitcnt vmcnt(9)
	ds_write_b128 v104, v[2:5]
	s_waitcnt vmcnt(8)
	ds_write_b128 v104, v[6:9] offset:8704
	s_waitcnt vmcnt(7)
	ds_write_b128 v104, v[10:13] offset:17408
	s_waitcnt vmcnt(6)
	ds_write_b128 v104, v[14:17] offset:26112
	s_waitcnt vmcnt(5)
	ds_write_b128 v105, v[18:21] offset:53248
	s_waitcnt vmcnt(4)
	ds_write_b128 v105, v[22:25] offset:62464
	s_branch .LBB0_786

.LBB0_1095:
	s_lshl_b64 s[50:51], s[52:53], 2
	v_lshl_or_b32 v178, s70, 8, v180
	s_add_u32 s50, s65, s50
	v_ashrrev_i32_e32 v179, 31, v178
	s_addc_u32 s51, s66, s51
	v_lshl_add_u64 v[134:135], v[158:159], 0, v[178:179]
	v_lshl_add_u64 v[130:131], v[178:179], 2, s[50:51]
	s_mov_b32 s6, 0x12000
	v_lshlrev_b64 v[134:135], 2, v[134:135]
	v_add_co_u32_e32 v132, vcc, s6, v130
	v_lshl_add_u64 v[150:151], s[14:15], 0, v[134:135]
	s_nop 0
	v_addc_co_u32_e32 v133, vcc, 0, v131, vcc
	global_load_dwordx4 v[138:141], v[132:133], off
	s_mov_b64 s[50:51], 0x12000
	v_lshl_add_u64 v[130:131], v[130:131], 0, s[50:51]
	v_lshl_add_u64 v[152:153], s[48:49], 0, v[134:135]
	global_load_dwordx4 v[142:145], v[130:131], off offset:64
	global_load_dwordx4 v[134:137], v[130:131], off offset:512
	s_nop 0
	global_load_dwordx4 v[130:133], v[130:131], off offset:576
	s_mov_b32 s70, s36
	s_mov_b32 s30, s42
	s_and_b64 vcc, exec, s[40:41]
	s_sub_u32 s50, s48, s14
	s_subb_u32 s51, s49, s15
	v_lshl_add_u64 v[146:147], v[158:159], 0, v[178:179]
	v_lshlrev_b64 v[146:147], 2, v[146:147]
	v_lshl_add_u64 v[146:147], s[14:15], 0, v[146:147]
	v_lshl_add_u64 v[148:149], v[160:161], 0, v[178:179]
	v_lshlrev_b64 v[148:149], 2, v[148:149]
	v_lshl_add_u64 v[148:149], s[14:15], 0, v[148:149]
	global_load_dwordx4 v[182:185], v[146:147], off
	global_load_dwordx4 v[186:189], v[146:147], off offset:64
	global_load_dwordx4 v[190:193], v[146:147], off offset:512
	global_load_dwordx4 v[194:197], v[146:147], off offset:576
	global_load_dwordx4 v[198:201], v[148:149], off
	global_load_dwordx4 v[202:205], v[148:149], off offset:64
	global_load_dwordx4 v[206:209], v[148:149], off offset:512
	global_load_dwordx4 v[210:213], v[148:149], off offset:576
	v_lshl_add_u64 v[214:215], v[146:147], 0, s[50:51]
	s_waitcnt vmcnt(7)
	v_pk_fma_f32 v[128:129], v[128:129], v[140:141], v[184:185]
	v_pk_fma_f32 v[126:127], v[126:127], v[138:139], v[182:183]
	global_store_dwordx4 v[214:215], v[126:129], off
	v_lshl_add_u64 v[150:151], v[162:163], 0, v[178:179]
	v_lshlrev_b64 v[150:151], 2, v[150:151]
	v_lshl_add_u64 v[150:151], s[14:15], 0, v[150:151]
	global_load_dwordx4 v[182:185], v[150:151], off
	s_waitcnt vmcnt(8)
	v_pk_fma_f32 v[124:125], v[124:125], v[144:145], v[188:189]
	v_pk_fma_f32 v[122:123], v[122:123], v[142:143], v[186:187]
	global_store_dwordx4 v[214:215], v[122:125], off offset:64
	global_load_dwordx4 v[186:189], v[150:151], off offset:64
	s_waitcnt vmcnt(9)
	v_pk_fma_f32 v[120:121], v[120:121], v[136:137], v[192:193]
	v_pk_fma_f32 v[118:119], v[118:119], v[134:135], v[190:191]
	global_store_dwordx4 v[214:215], v[118:121], off offset:512
	global_load_dwordx4 v[190:193], v[150:151], off offset:512
	s_waitcnt vmcnt(10)
	v_pk_fma_f32 v[108:109], v[108:109], v[132:133], v[196:197]
	v_pk_fma_f32 v[106:107], v[106:107], v[130:131], v[194:195]
	global_store_dwordx4 v[214:215], v[106:109], off offset:576
	global_load_dwordx4 v[194:197], v[150:151], off offset:576
	v_lshl_add_u64 v[216:217], v[148:149], 0, s[50:51]
	s_waitcnt vmcnt(11)
	v_pk_fma_f32 v[116:117], v[116:117], v[140:141], v[200:201]
	v_pk_fma_f32 v[114:115], v[114:115], v[138:139], v[198:199]
	global_store_dwordx4 v[216:217], v[114:117], off
	v_lshl_add_u64 v[152:153], v[164:165], 0, v[178:179]
	v_lshlrev_b64 v[152:153], 2, v[152:153]
	v_lshl_add_u64 v[152:153], s[14:15], 0, v[152:153]
	global_load_dwordx4 v[198:201], v[152:153], off
	s_waitcnt vmcnt(12)
	v_pk_fma_f32 v[112:113], v[112:113], v[144:145], v[204:205]
	v_pk_fma_f32 v[110:111], v[110:111], v[142:143], v[202:203]
	global_store_dwordx4 v[216:217], v[110:113], off offset:64
	global_load_dwordx4 v[202:205], v[152:153], off offset:64
	s_waitcnt vmcnt(13)
	v_pk_fma_f32 v[104:105], v[104:105], v[136:137], v[208:209]
	v_pk_fma_f32 v[102:103], v[102:103], v[134:135], v[206:207]
	global_store_dwordx4 v[216:217], v[102:105], off offset:512
	global_load_dwordx4 v[206:209], v[152:153], off offset:512
	s_waitcnt vmcnt(14)
	v_pk_fma_f32 v[92:93], v[92:93], v[132:133], v[212:213]
	v_pk_fma_f32 v[90:91], v[90:91], v[130:131], v[210:211]
	global_store_dwordx4 v[216:217], v[90:93], off offset:576
	global_load_dwordx4 v[210:213], v[152:153], off offset:576
	v_lshl_add_u64 v[214:215], v[150:151], 0, s[50:51]
	s_waitcnt vmcnt(14)
	v_pk_fma_f32 v[100:101], v[100:101], v[140:141], v[184:185]
	v_pk_fma_f32 v[98:99], v[98:99], v[138:139], v[182:183]
	global_store_dwordx4 v[214:215], v[98:101], off
	v_lshl_add_u64 v[146:147], v[166:167], 0, v[178:179]
	v_lshlrev_b64 v[146:147], 2, v[146:147]
	v_lshl_add_u64 v[146:147], s[14:15], 0, v[146:147]
	global_load_dwordx4 v[182:185], v[146:147], off
	s_waitcnt vmcnt(14)
	v_pk_fma_f32 v[96:97], v[96:97], v[144:145], v[188:189]
	v_pk_fma_f32 v[94:95], v[94:95], v[142:143], v[186:187]
	global_store_dwordx4 v[214:215], v[94:97], off offset:64
	global_load_dwordx4 v[186:189], v[146:147], off offset:64
	s_waitcnt vmcnt(14)
	v_pk_fma_f32 v[88:89], v[88:89], v[136:137], v[192:193]
	v_pk_fma_f32 v[86:87], v[86:87], v[134:135], v[190:191]
	global_store_dwordx4 v[214:215], v[86:89], off offset:512
	global_load_dwordx4 v[190:193], v[146:147], off offset:512
	s_waitcnt vmcnt(14)
	v_pk_fma_f32 v[76:77], v[76:77], v[132:133], v[196:197]
	v_pk_fma_f32 v[74:75], v[74:75], v[130:131], v[194:195]
	global_store_dwordx4 v[214:215], v[74:77], off offset:576
	global_load_dwordx4 v[194:197], v[146:147], off offset:576
	v_lshl_add_u64 v[216:217], v[152:153], 0, s[50:51]
	s_waitcnt vmcnt(14)
	v_pk_fma_f32 v[84:85], v[84:85], v[140:141], v[200:201]
	v_pk_fma_f32 v[82:83], v[82:83], v[138:139], v[198:199]
	global_store_dwordx4 v[216:217], v[82:85], off
	v_lshl_add_u64 v[148:149], v[168:169], 0, v[178:179]
	v_lshlrev_b64 v[148:149], 2, v[148:149]
	v_lshl_add_u64 v[148:149], s[14:15], 0, v[148:149]
	global_load_dwordx4 v[198:201], v[148:149], off
	s_waitcnt vmcnt(14)
	v_pk_fma_f32 v[80:81], v[80:81], v[144:145], v[204:205]
	v_pk_fma_f32 v[78:79], v[78:79], v[142:143], v[202:203]
	global_store_dwordx4 v[216:217], v[78:81], off offset:64
	global_load_dwordx4 v[202:205], v[148:149], off offset:64
	s_waitcnt vmcnt(14)
	v_pk_fma_f32 v[72:73], v[72:73], v[136:137], v[208:209]
	v_pk_fma_f32 v[70:71], v[70:71], v[134:135], v[206:207]
	global_store_dwordx4 v[216:217], v[70:73], off offset:512
	global_load_dwordx4 v[206:209], v[148:149], off offset:512
	s_waitcnt vmcnt(14)
	v_pk_fma_f32 v[68:69], v[68:69], v[132:133], v[212:213]
	v_pk_fma_f32 v[66:67], v[66:67], v[130:131], v[210:211]
	global_store_dwordx4 v[216:217], v[66:69], off offset:576
	global_load_dwordx4 v[210:213], v[148:149], off offset:576
	v_lshl_add_u64 v[214:215], v[146:147], 0, s[50:51]
	s_waitcnt vmcnt(14)
	v_pk_fma_f32 v[64:65], v[64:65], v[140:141], v[184:185]
	v_pk_fma_f32 v[62:63], v[62:63], v[138:139], v[182:183]
	global_store_dwordx4 v[214:215], v[62:65], off
	v_lshl_add_u64 v[150:151], v[170:171], 0, v[178:179]
	v_lshlrev_b64 v[150:151], 2, v[150:151]
	v_lshl_add_u64 v[150:151], s[14:15], 0, v[150:151]
	global_load_dwordx4 v[182:185], v[150:151], off
	s_waitcnt vmcnt(14)
	v_pk_fma_f32 v[60:61], v[60:61], v[144:145], v[188:189]
	v_pk_fma_f32 v[58:59], v[58:59], v[142:143], v[186:187]
	global_store_dwordx4 v[214:215], v[58:61], off offset:64
	global_load_dwordx4 v[186:189], v[150:151], off offset:64
	s_waitcnt vmcnt(14)
	v_pk_fma_f32 v[56:57], v[56:57], v[136:137], v[192:193]
	v_pk_fma_f32 v[54:55], v[54:55], v[134:135], v[190:191]
	global_store_dwordx4 v[214:215], v[54:57], off offset:512
	global_load_dwordx4 v[190:193], v[150:151], off offset:512
	s_waitcnt vmcnt(14)
	v_pk_fma_f32 v[44:45], v[44:45], v[132:133], v[196:197]
	v_pk_fma_f32 v[42:43], v[42:43], v[130:131], v[194:195]
	global_store_dwordx4 v[214:215], v[42:45], off offset:576
	global_load_dwordx4 v[194:197], v[150:151], off offset:576
	v_lshl_add_u64 v[216:217], v[148:149], 0, s[50:51]
	s_waitcnt vmcnt(14)
	v_pk_fma_f32 v[52:53], v[52:53], v[140:141], v[200:201]
	v_pk_fma_f32 v[50:51], v[50:51], v[138:139], v[198:199]
	global_store_dwordx4 v[216:217], v[50:53], off
	v_lshl_add_u64 v[152:153], v[172:173], 0, v[178:179]
	v_lshlrev_b64 v[152:153], 2, v[152:153]
	v_lshl_add_u64 v[152:153], s[14:15], 0, v[152:153]
	global_load_dwordx4 v[198:201], v[152:153], off
	s_waitcnt vmcnt(14)
	v_pk_fma_f32 v[48:49], v[48:49], v[144:145], v[204:205]
	v_pk_fma_f32 v[46:47], v[46:47], v[142:143], v[202:203]
	global_store_dwordx4 v[216:217], v[46:49], off offset:64
	global_load_dwordx4 v[202:205], v[152:153], off offset:64
	s_waitcnt vmcnt(14)
	v_pk_fma_f32 v[40:41], v[40:41], v[136:137], v[208:209]
	v_pk_fma_f32 v[38:39], v[38:39], v[134:135], v[206:207]
	global_store_dwordx4 v[216:217], v[38:41], off offset:512
	global_load_dwordx4 v[206:209], v[152:153], off offset:512
	s_waitcnt vmcnt(14)
	v_pk_fma_f32 v[28:29], v[28:29], v[132:133], v[212:213]
	v_pk_fma_f32 v[26:27], v[26:27], v[130:131], v[210:211]
	global_store_dwordx4 v[216:217], v[26:29], off offset:576
	global_load_dwordx4 v[210:213], v[152:153], off offset:576
	v_lshl_add_u64 v[214:215], v[150:151], 0, s[50:51]
	s_waitcnt vmcnt(14)
	v_pk_fma_f32 v[36:37], v[36:37], v[140:141], v[184:185]
	v_pk_fma_f32 v[34:35], v[34:35], v[138:139], v[182:183]
	global_store_dwordx4 v[214:215], v[34:37], off
	s_waitcnt vmcnt(13)
	v_pk_fma_f32 v[32:33], v[32:33], v[144:145], v[188:189]
	v_pk_fma_f32 v[30:31], v[30:31], v[142:143], v[186:187]
	global_store_dwordx4 v[214:215], v[30:33], off offset:64
	s_waitcnt vmcnt(12)
	v_pk_fma_f32 v[24:25], v[24:25], v[136:137], v[192:193]
	v_pk_fma_f32 v[22:23], v[22:23], v[134:135], v[190:191]
	global_store_dwordx4 v[214:215], v[22:25], off offset:512
	s_waitcnt vmcnt(11)
	v_pk_fma_f32 v[12:13], v[12:13], v[132:133], v[196:197]
	v_pk_fma_f32 v[10:11], v[10:11], v[130:131], v[194:195]
	global_store_dwordx4 v[214:215], v[10:13], off offset:576
	v_lshl_add_u64 v[216:217], v[152:153], 0, s[50:51]
	s_waitcnt vmcnt(10)
	v_pk_fma_f32 v[20:21], v[20:21], v[140:141], v[200:201]
	v_pk_fma_f32 v[18:19], v[18:19], v[138:139], v[198:199]
	global_store_dwordx4 v[216:217], v[18:21], off
	s_waitcnt vmcnt(9)
	v_pk_fma_f32 v[16:17], v[16:17], v[144:145], v[204:205]
	v_pk_fma_f32 v[14:15], v[14:15], v[142:143], v[202:203]
	global_store_dwordx4 v[216:217], v[14:17], off offset:64
	s_waitcnt vmcnt(8)
	v_pk_fma_f32 v[8:9], v[8:9], v[136:137], v[208:209]
	v_pk_fma_f32 v[6:7], v[6:7], v[134:135], v[206:207]
	global_store_dwordx4 v[216:217], v[6:9], off offset:512
	s_waitcnt vmcnt(7)
	v_pk_fma_f32 v[4:5], v[4:5], v[132:133], v[212:213]
	v_pk_fma_f32 v[2:3], v[2:3], v[130:131], v[210:211]
	global_store_dwordx4 v[216:217], v[2:5], off offset:576
	s_mov_b64 s[14:15], s[46:47]
	s_mov_b64 s[48:49], s[44:45]
	s_cbranch_vccnz .LBB0_1112
